# grid barrier: the XCD leader (last local arriver, so its XCD is idle) invalidates right after its writeback, before the cross-XCD arrival; no invalidate between the global and the local release
# speedup vs baseline: 1.0134x; 1.0045x over previous
; __device__ __forceinline__ unsigned xb_add(unsigned* p, unsigned v) { return __hip_atomic_fetch_add(p, v, __ATOMIC_RELAXED, __HIP_MEMORY_SCOPE_AGENT); }
; __device__ __forceinline__ void xcd_barrier(const XcdBarrier& b) {
;     ...
;         if (old + 1u == (gen + 1u) * nloc) {
;             __builtin_amdgcn_fence(__ATOMIC_RELEASE, "agent");
;             asm volatile("s_waitcnt vmcnt(0)" ::: "memory");
;             const unsigned og = xb_add(&bar[XB_TOP], 1u);
.LBB0_139:
	s_andn2_saveexec_b64 s[6:7], s[6:7]
	s_cbranch_execz .LBB0_159
	s_mov_b64 s[6:7], exec
	buffer_wbl2 sc1
	s_waitcnt lgkmcnt(0)
	s_waitcnt vmcnt(0)
	buffer_inv sc1
	v_mbcnt_lo_u32_b32 v1, s6, 0
	v_mbcnt_hi_u32_b32 v1, s7, v1
	v_cmp_eq_u32_e32 vcc, 0, v1
	s_and_saveexec_b64 s[8:9], vcc
	s_cbranch_execz .LBB0_142
	s_bcnt1_i32_b64 s3, s[6:7]
	v_mov_b32_e32 v2, 0x2f83000
	v_mov_b32_e32 v3, s3
	global_atomic_add v2, v2, v3, s[58:59] offset:1024 sc0

; __device__ __forceinline__ unsigned xb_add(unsigned* p, unsigned v) { return __hip_atomic_fetch_add(p, v, __ATOMIC_RELAXED, __HIP_MEMORY_SCOPE_AGENT); }
; __device__ __forceinline__ void xcd_barrier(const XcdBarrier& b) {
;     ...
;             __builtin_amdgcn_fence(__ATOMIC_ACQUIRE, "agent");
;             xb_add(&bar[XB_XGEN(b.x)], 1u);
;             asm volatile("s_waitcnt vmcnt(0)" ::: "memory");
.LBB0_156:
	s_or_b64 exec, exec, s[6:7]
	s_mov_b64 s[6:7], exec
	v_mbcnt_lo_u32_b32 v0, s6, 0
	v_mbcnt_hi_u32_b32 v0, s7, v0
	v_cmp_eq_u32_e32 vcc, 0, v0
	s_waitcnt vmcnt(0)
	s_and_saveexec_b64 s[8:9], vcc
	s_cbranch_execz .LBB0_158
	s_bcnt1_i32_b64 s3, s[6:7]
	v_mov_b32_e32 v0, 0x2000
	v_mov_b32_e32 v1, s3
	global_atomic_add v0, v1, s[4:5] offset:1024

; __device__ __forceinline__ unsigned xb_add(unsigned* p, unsigned v) { return __hip_atomic_fetch_add(p, v, __ATOMIC_RELAXED, __HIP_MEMORY_SCOPE_AGENT); }
; __device__ __forceinline__ void xcd_barrier(const XcdBarrier& b) {
;     ...
;         if (old + 1u == (gen + 1u) * nloc) {
;             __builtin_amdgcn_fence(__ATOMIC_RELEASE, "agent");
;             asm volatile("s_waitcnt vmcnt(0)" ::: "memory");
;             const unsigned og = xb_add(&bar[XB_TOP], 1u);
.LBB0_1057:
	s_andn2_saveexec_b64 s[6:7], s[6:7]
	s_cbranch_execz .LBB0_1077
	s_mov_b64 s[6:7], exec
	buffer_wbl2 sc1
	s_waitcnt lgkmcnt(0)
	s_waitcnt vmcnt(0)
	buffer_inv sc1
	v_mbcnt_lo_u32_b32 v1, s6, 0
	v_mbcnt_hi_u32_b32 v1, s7, v1
	v_cmp_eq_u32_e32 vcc, 0, v1
	s_and_saveexec_b64 s[10:11], vcc
	s_cbranch_execz .LBB0_1060
	s_bcnt1_i32_b64 s3, s[6:7]
	v_mov_b32_e32 v2, 0x2f83000
	v_mov_b32_e32 v3, s3
	global_atomic_add v2, v2, v3, s[58:59] offset:1024 sc0

; __device__ __forceinline__ unsigned xb_add(unsigned* p, unsigned v) { return __hip_atomic_fetch_add(p, v, __ATOMIC_RELAXED, __HIP_MEMORY_SCOPE_AGENT); }
; __device__ __forceinline__ void xcd_barrier(const XcdBarrier& b) {
;     ...
;             __builtin_amdgcn_fence(__ATOMIC_ACQUIRE, "agent");
;             xb_add(&bar[XB_XGEN(b.x)], 1u);
;             asm volatile("s_waitcnt vmcnt(0)" ::: "memory");
.LBB0_1074:
	s_or_b64 exec, exec, s[6:7]
	s_mov_b64 s[6:7], exec
	v_mbcnt_lo_u32_b32 v0, s6, 0
	v_mbcnt_hi_u32_b32 v0, s7, v0
	v_cmp_eq_u32_e32 vcc, 0, v0
	s_waitcnt vmcnt(0)
	s_and_saveexec_b64 s[10:11], vcc
	s_cbranch_execz .LBB0_1076
	s_bcnt1_i32_b64 s3, s[6:7]
	v_mov_b32_e32 v0, 0x2000
	v_mov_b32_e32 v1, s3
	global_atomic_add v0, v1, s[4:5] offset:1024

; __device__ __forceinline__ unsigned xb_add(unsigned* p, unsigned v) { return __hip_atomic_fetch_add(p, v, __ATOMIC_RELAXED, __HIP_MEMORY_SCOPE_AGENT); }
; __device__ __forceinline__ void xcd_barrier(const XcdBarrier& b) {
;     ...
;         if (old + 1u == (gen + 1u) * nloc) {
;             __builtin_amdgcn_fence(__ATOMIC_RELEASE, "agent");
;             asm volatile("s_waitcnt vmcnt(0)" ::: "memory");
;             const unsigned og = xb_add(&bar[XB_TOP], 1u);
.LBB0_1202:
	s_andn2_saveexec_b64 s[4:5], s[4:5]
	s_cbranch_execz .LBB0_1222
	s_mov_b64 s[4:5], exec
	buffer_wbl2 sc1
	s_waitcnt lgkmcnt(0)
	s_waitcnt vmcnt(0)
	buffer_inv sc1
	v_mbcnt_lo_u32_b32 v1, s4, 0
	v_mbcnt_hi_u32_b32 v1, s5, v1
	v_cmp_eq_u32_e32 vcc, 0, v1
	s_and_saveexec_b64 s[6:7], vcc
	s_cbranch_execz .LBB0_1205
	s_bcnt1_i32_b64 s4, s[4:5]
	v_mov_b32_e32 v2, 0x2f83000
	v_mov_b32_e32 v3, s4
	global_atomic_add v2, v2, v3, s[58:59] offset:1024 sc0

; __device__ __forceinline__ unsigned xb_add(unsigned* p, unsigned v) { return __hip_atomic_fetch_add(p, v, __ATOMIC_RELAXED, __HIP_MEMORY_SCOPE_AGENT); }
; __device__ __forceinline__ void xcd_barrier(const XcdBarrier& b) {
;     ...
;             __builtin_amdgcn_fence(__ATOMIC_ACQUIRE, "agent");
;             xb_add(&bar[XB_XGEN(b.x)], 1u);
;             asm volatile("s_waitcnt vmcnt(0)" ::: "memory");
.LBB0_1219:
	s_or_b64 exec, exec, s[4:5]
	s_mov_b64 s[4:5], exec
	v_mbcnt_lo_u32_b32 v0, s4, 0
	v_mbcnt_hi_u32_b32 v0, s5, v0
	v_cmp_eq_u32_e32 vcc, 0, v0
	s_waitcnt vmcnt(0)
	s_and_saveexec_b64 s[6:7], vcc
	s_cbranch_execz .LBB0_1221
	s_bcnt1_i32_b64 s4, s[4:5]
	v_mov_b32_e32 v0, 0x2000
	v_mov_b32_e32 v1, s4
	global_atomic_add v0, v1, s[2:3] offset:1024
